# weight conversion (fragment-major part): all of a workgroup's tile loads of a matrix issued before the per-tile transpose / store (was one exposed load round trip per tile)
# speedup vs baseline: 1.0068x; 1.0068x over previous
.LBB0_786:
	v_readlane_b32 s0, v235, 17
	v_readlane_b32 s1, v235, 18
	s_mov_b32 s1, s9
	v_writelane_b32 v235, s0, 17
	s_mov_b64 s[2:3], 0
	v_readlane_b32 s4, v246, 13
	v_writelane_b32 v235, s1, 18
	s_add_u32 s0, s26, s2
	v_readlane_b32 s5, v246, 14
	s_addc_u32 s1, s27, s3
	v_mov_b32_e32 v4, v163
	s_andn2_b64 vcc, exec, s[4:5]
	s_movk_i32 s31, 0x7080
	s_cbranch_vccnz .LBB0_789
	v_readlane_b32 s2, v235, 17
	s_mul_hi_u32 s3, s2, 0x1c20000
	s_mul_i32 s2, s2, 0x1c20000
	s_add_u32 s2, s68, s2
	s_addc_u32 s3, s69, s3
	s_add_u32 s4, s26, 0xeb20000
	s_addc_u32 s5, s27, 0
	v_lshrrev_b32_e32 v2, 3, v163
	v_and_b32_e32 v3, 7, v163
	v_lshlrev_b32_e32 v3, 4, v3
	s_mov_b32 s0, 0x7080
	v_mul_lo_u32 v4, v2, s0
	v_add_u32_e32 v4, v4, v3
	v_add_u32_e32 v5, 0xe1000, v4
	s_movk_i32 s0, 0x84
	v_mul_lo_u32 v6, v2, s0
	v_add_u32_e32 v6, v6, v3
	v_and_b32_e32 v9, 31, v163
	v_lshrrev_b32_e32 v18, 5, v163
	s_movk_i32 s0, 0x420
	v_mul_lo_u32 v7, v18, s0
	v_lshl_add_u32 v7, v9, 2, v7
	v_lshrrev_b32_e32 v19, 4, v9
	s_mov_b32 s0, 0x8000
	v_mul_lo_u32 v8, v19, s0
	v_lshrrev_b32_e32 v19, 2, v18
	v_lshl_add_u32 v8, v19, 10, v8
	v_and_b32_e32 v19, 3, v18
	v_lshl_add_u32 v8, v19, 8, v8
	v_and_b32_e32 v19, 15, v9
	v_lshl_add_u32 v8, v19, 4, v8
	v_readlane_b32 s6, v246, 0
	s_add_i32 s31, s6, 0x0
	s_mul_hi_u32 s7, s31, 0x1234568
	s_mul_i32 s8, s7, 225
	s_sub_u32 s8, s31, s8
	s_mul_i32 s0, s7, 0x1c2000
	s_mul_hi_u32 s1, s7, 0x1c2000
	s_lshl_b32 s29, s8, 7
	s_add_u32 s0, s0, s29
	s_addc_u32 s1, s1, 0
	s_add_u32 s0, s2, s0
	s_addc_u32 s1, s3, s1
	s_sub_u32 s29, s8, 1
	s_cmp_lt_u32 s8, 128
	s_cselect_b32 s29, s8, s29
	s_cmp_eq_u32 s8, 128
	s_cselect_b32 s29, 224, s29
	s_lshl_b32 s29, s29, 16
	s_lshl_b32 s30, s7, 11
	s_add_u32 s29, s29, s30
	global_load_dwordx4 v[32:35], v4, s[0:1]
	global_load_dwordx4 v[36:39], v5, s[0:1]
	s_add_i32 s31, s6, 0x200
	s_mul_hi_u32 s7, s31, 0x1234568
	s_mul_i32 s8, s7, 225
	s_sub_u32 s8, s31, s8
	s_mul_i32 s0, s7, 0x1c2000
	s_mul_hi_u32 s1, s7, 0x1c2000
	s_lshl_b32 s29, s8, 7
	s_add_u32 s0, s0, s29
	s_addc_u32 s1, s1, 0
	s_add_u32 s0, s2, s0
	s_addc_u32 s1, s3, s1
	s_sub_u32 s29, s8, 1
	s_cmp_lt_u32 s8, 128
	s_cselect_b32 s29, s8, s29
	s_cmp_eq_u32 s8, 128
	s_cselect_b32 s29, 224, s29
	s_lshl_b32 s29, s29, 16
	s_lshl_b32 s30, s7, 11
	s_add_u32 s29, s29, s30
	global_load_dwordx4 v[40:43], v4, s[0:1]
	global_load_dwordx4 v[44:47], v5, s[0:1]
	s_add_i32 s31, s6, 0x400
	s_mul_hi_u32 s7, s31, 0x1234568
	s_mul_i32 s8, s7, 225
	s_sub_u32 s8, s31, s8
	s_mul_i32 s0, s7, 0x1c2000
	s_mul_hi_u32 s1, s7, 0x1c2000
	s_lshl_b32 s29, s8, 7
	s_add_u32 s0, s0, s29
	s_addc_u32 s1, s1, 0
	s_add_u32 s0, s2, s0
	s_addc_u32 s1, s3, s1
	s_sub_u32 s29, s8, 1
	s_cmp_lt_u32 s8, 128
	s_cselect_b32 s29, s8, s29
	s_cmp_eq_u32 s8, 128
	s_cselect_b32 s29, 224, s29
	s_lshl_b32 s29, s29, 16
	s_lshl_b32 s30, s7, 11
	s_add_u32 s29, s29, s30
	global_load_dwordx4 v[48:51], v4, s[0:1]
	global_load_dwordx4 v[52:55], v5, s[0:1]
	s_add_i32 s31, s6, 0x600
	s_mul_hi_u32 s7, s31, 0x1234568
	s_mul_i32 s8, s7, 225
	s_sub_u32 s8, s31, s8
	s_mul_i32 s0, s7, 0x1c2000
	s_mul_hi_u32 s1, s7, 0x1c2000
	s_lshl_b32 s29, s8, 7
	s_add_u32 s0, s0, s29
	s_addc_u32 s1, s1, 0
	s_add_u32 s0, s2, s0
	s_addc_u32 s1, s3, s1
	s_sub_u32 s29, s8, 1
	s_cmp_lt_u32 s8, 128
	s_cselect_b32 s29, s8, s29
	s_cmp_eq_u32 s8, 128
	s_cselect_b32 s29, 224, s29
	s_lshl_b32 s29, s29, 16
	s_lshl_b32 s30, s7, 11
	s_add_u32 s29, s29, s30
	global_load_dwordx4 v[56:59], v4, s[0:1]
	global_load_dwordx4 v[60:63], v5, s[0:1]
	s_add_i32 s31, s6, 0x800
	s_mul_hi_u32 s7, s31, 0x1234568
	s_mul_i32 s8, s7, 225
	s_sub_u32 s8, s31, s8
	s_mul_i32 s0, s7, 0x1c2000
	s_mul_hi_u32 s1, s7, 0x1c2000
	s_lshl_b32 s29, s8, 7
	s_add_u32 s0, s0, s29
	s_addc_u32 s1, s1, 0
	s_add_u32 s0, s2, s0
	s_addc_u32 s1, s3, s1
	s_sub_u32 s29, s8, 1
	s_cmp_lt_u32 s8, 128
	s_cselect_b32 s29, s8, s29
	s_cmp_eq_u32 s8, 128
	s_cselect_b32 s29, 224, s29
	s_lshl_b32 s29, s29, 16
	s_lshl_b32 s30, s7, 11
	s_add_u32 s29, s29, s30
	global_load_dwordx4 v[64:67], v4, s[0:1]
	global_load_dwordx4 v[68:71], v5, s[0:1]
	s_add_i32 s31, s6, 0xa00
	s_mul_hi_u32 s7, s31, 0x1234568
	s_mul_i32 s8, s7, 225
	s_sub_u32 s8, s31, s8
	s_mul_i32 s0, s7, 0x1c2000
	s_mul_hi_u32 s1, s7, 0x1c2000
	s_lshl_b32 s29, s8, 7
	s_add_u32 s0, s0, s29
	s_addc_u32 s1, s1, 0
	s_add_u32 s0, s2, s0
	s_addc_u32 s1, s3, s1
	s_sub_u32 s29, s8, 1
	s_cmp_lt_u32 s8, 128
	s_cselect_b32 s29, s8, s29
	s_cmp_eq_u32 s8, 128
	s_cselect_b32 s29, 224, s29
	s_lshl_b32 s29, s29, 16
	s_lshl_b32 s30, s7, 11
	s_add_u32 s29, s29, s30
	global_load_dwordx4 v[72:75], v4, s[0:1]
	global_load_dwordx4 v[76:79], v5, s[0:1]
	s_add_i32 s31, s6, 0xc00
	s_mul_hi_u32 s7, s31, 0x1234568
	s_mul_i32 s8, s7, 225
	s_sub_u32 s8, s31, s8
	s_mul_i32 s0, s7, 0x1c2000
	s_mul_hi_u32 s1, s7, 0x1c2000
	s_lshl_b32 s29, s8, 7
	s_add_u32 s0, s0, s29
	s_addc_u32 s1, s1, 0
	s_add_u32 s0, s2, s0
	s_addc_u32 s1, s3, s1
	s_sub_u32 s29, s8, 1
	s_cmp_lt_u32 s8, 128
	s_cselect_b32 s29, s8, s29
	s_cmp_eq_u32 s8, 128
	s_cselect_b32 s29, 224, s29
	s_lshl_b32 s29, s29, 16
	s_lshl_b32 s30, s7, 11
	s_add_u32 s29, s29, s30
	global_load_dwordx4 v[80:83], v4, s[0:1]
	global_load_dwordx4 v[84:87], v5, s[0:1]
	s_add_i32 s31, s6, 0xe00
	s_cmp_lt_u32 s31, 3600
	s_cbranch_scc0 .Lfm_a_win_issued
	s_mul_hi_u32 s7, s31, 0x1234568
	s_mul_i32 s8, s7, 225
	s_sub_u32 s8, s31, s8
	s_mul_i32 s0, s7, 0x1c2000
	s_mul_hi_u32 s1, s7, 0x1c2000
	s_lshl_b32 s29, s8, 7
	s_add_u32 s0, s0, s29
	s_addc_u32 s1, s1, 0
	s_add_u32 s0, s2, s0
	s_addc_u32 s1, s3, s1
	s_sub_u32 s29, s8, 1
	s_cmp_lt_u32 s8, 128
	s_cselect_b32 s29, s8, s29
	s_cmp_eq_u32 s8, 128
	s_cselect_b32 s29, 224, s29
	s_lshl_b32 s29, s29, 16
	s_lshl_b32 s30, s7, 11
	s_add_u32 s29, s29, s30
	global_load_dwordx4 v[88:91], v4, s[0:1]
	global_load_dwordx4 v[92:95], v5, s[0:1]
.Lfm_a_win_issued:
	s_add_i32 s31, s6, 0x0
	s_mul_hi_u32 s7, s31, 0x1234568
	s_mul_i32 s8, s7, 225
	s_sub_u32 s8, s31, s8
	s_mul_i32 s0, s7, 0x1c2000
	s_mul_hi_u32 s1, s7, 0x1c2000
	s_lshl_b32 s29, s8, 7
	s_add_u32 s0, s0, s29
	s_addc_u32 s1, s1, 0
	s_add_u32 s0, s2, s0
	s_addc_u32 s1, s3, s1
	s_sub_u32 s29, s8, 1
	s_cmp_lt_u32 s8, 128
	s_cselect_b32 s29, s8, s29
	s_cmp_eq_u32 s8, 128
	s_cselect_b32 s29, 224, s29
	s_lshl_b32 s29, s29, 16
	s_lshl_b32 s30, s7, 11
	s_add_u32 s29, s29, s30
	s_waitcnt vmcnt(12)
	s_barrier
	ds_write2_b32 v6, v32, v33 offset1:1
	ds_write2_b32 v6, v34, v35 offset0:2 offset1:3
	v_add_u32_e32 v19, 0x1080, v6
	ds_write2_b32 v19, v36, v37 offset1:1
	ds_write2_b32 v19, v38, v39 offset0:2 offset1:3
	s_waitcnt lgkmcnt(0)
	s_barrier
	ds_read_b32 v20, v7
	ds_read_b32 v21, v7 offset:132
	ds_read_b32 v22, v7 offset:264
	ds_read_b32 v23, v7 offset:396
	ds_read_b32 v24, v7 offset:528
	ds_read_b32 v25, v7 offset:660
	ds_read_b32 v26, v7 offset:792
	ds_read_b32 v27, v7 offset:924
	s_waitcnt lgkmcnt(0)
	v_cvt_pk_bf16_f32 v28, v20, v21
	v_cvt_pk_bf16_f32 v29, v22, v23
	v_cvt_pk_bf16_f32 v30, v24, v25
	v_cvt_pk_bf16_f32 v31, v26, v27
	s_add_u32 s0, s4, s29
	s_addc_u32 s1, s5, 0
	global_store_dwordx4 v8, v[28:31], s[0:1]
	s_add_i32 s31, s6, 0x200
	s_mul_hi_u32 s7, s31, 0x1234568
	s_mul_i32 s8, s7, 225
	s_sub_u32 s8, s31, s8
	s_mul_i32 s0, s7, 0x1c2000
	s_mul_hi_u32 s1, s7, 0x1c2000
	s_lshl_b32 s29, s8, 7
	s_add_u32 s0, s0, s29
	s_addc_u32 s1, s1, 0
	s_add_u32 s0, s2, s0
	s_addc_u32 s1, s3, s1
	s_sub_u32 s29, s8, 1
	s_cmp_lt_u32 s8, 128
	s_cselect_b32 s29, s8, s29
	s_cmp_eq_u32 s8, 128
	s_cselect_b32 s29, 224, s29
	s_lshl_b32 s29, s29, 16
	s_lshl_b32 s30, s7, 11
	s_add_u32 s29, s29, s30
	s_waitcnt vmcnt(11)
	s_barrier
	ds_write2_b32 v6, v40, v41 offset1:1
	ds_write2_b32 v6, v42, v43 offset0:2 offset1:3
	v_add_u32_e32 v19, 0x1080, v6
	ds_write2_b32 v19, v44, v45 offset1:1
	ds_write2_b32 v19, v46, v47 offset0:2 offset1:3
	s_waitcnt lgkmcnt(0)
	s_barrier
	ds_read_b32 v20, v7
	ds_read_b32 v21, v7 offset:132
	ds_read_b32 v22, v7 offset:264
	ds_read_b32 v23, v7 offset:396
	ds_read_b32 v24, v7 offset:528
	ds_read_b32 v25, v7 offset:660
	ds_read_b32 v26, v7 offset:792
	ds_read_b32 v27, v7 offset:924
	s_waitcnt lgkmcnt(0)
	v_cvt_pk_bf16_f32 v28, v20, v21
	v_cvt_pk_bf16_f32 v29, v22, v23
	v_cvt_pk_bf16_f32 v30, v24, v25
	v_cvt_pk_bf16_f32 v31, v26, v27
	s_add_u32 s0, s4, s29
	s_addc_u32 s1, s5, 0
	global_store_dwordx4 v8, v[28:31], s[0:1]
	s_add_i32 s31, s6, 0x400
	s_mul_hi_u32 s7, s31, 0x1234568
	s_mul_i32 s8, s7, 225
	s_sub_u32 s8, s31, s8
	s_mul_i32 s0, s7, 0x1c2000
	s_mul_hi_u32 s1, s7, 0x1c2000
	s_lshl_b32 s29, s8, 7
	s_add_u32 s0, s0, s29
	s_addc_u32 s1, s1, 0
	s_add_u32 s0, s2, s0
	s_addc_u32 s1, s3, s1
	s_sub_u32 s29, s8, 1
	s_cmp_lt_u32 s8, 128
	s_cselect_b32 s29, s8, s29
	s_cmp_eq_u32 s8, 128
	s_cselect_b32 s29, 224, s29
	s_lshl_b32 s29, s29, 16
	s_lshl_b32 s30, s7, 11
	s_add_u32 s29, s29, s30
	s_waitcnt vmcnt(10)
	s_barrier
	ds_write2_b32 v6, v48, v49 offset1:1
	ds_write2_b32 v6, v50, v51 offset0:2 offset1:3
	v_add_u32_e32 v19, 0x1080, v6
	ds_write2_b32 v19, v52, v53 offset1:1
	ds_write2_b32 v19, v54, v55 offset0:2 offset1:3
	s_waitcnt lgkmcnt(0)
	s_barrier
	ds_read_b32 v20, v7
	ds_read_b32 v21, v7 offset:132
	ds_read_b32 v22, v7 offset:264
	ds_read_b32 v23, v7 offset:396
	ds_read_b32 v24, v7 offset:528
	ds_read_b32 v25, v7 offset:660
	ds_read_b32 v26, v7 offset:792
	ds_read_b32 v27, v7 offset:924
	s_waitcnt lgkmcnt(0)
	v_cvt_pk_bf16_f32 v28, v20, v21
	v_cvt_pk_bf16_f32 v29, v22, v23
	v_cvt_pk_bf16_f32 v30, v24, v25
	v_cvt_pk_bf16_f32 v31, v26, v27
	s_add_u32 s0, s4, s29
	s_addc_u32 s1, s5, 0
	global_store_dwordx4 v8, v[28:31], s[0:1]
	s_add_i32 s31, s6, 0x600
	s_mul_hi_u32 s7, s31, 0x1234568
	s_mul_i32 s8, s7, 225
	s_sub_u32 s8, s31, s8
	s_mul_i32 s0, s7, 0x1c2000
	s_mul_hi_u32 s1, s7, 0x1c2000
	s_lshl_b32 s29, s8, 7
	s_add_u32 s0, s0, s29
	s_addc_u32 s1, s1, 0
	s_add_u32 s0, s2, s0
	s_addc_u32 s1, s3, s1
	s_sub_u32 s29, s8, 1
	s_cmp_lt_u32 s8, 128
	s_cselect_b32 s29, s8, s29
	s_cmp_eq_u32 s8, 128
	s_cselect_b32 s29, 224, s29
	s_lshl_b32 s29, s29, 16
	s_lshl_b32 s30, s7, 11
	s_add_u32 s29, s29, s30
	s_waitcnt vmcnt(9)
	s_barrier
	ds_write2_b32 v6, v56, v57 offset1:1
	ds_write2_b32 v6, v58, v59 offset0:2 offset1:3
	v_add_u32_e32 v19, 0x1080, v6
	ds_write2_b32 v19, v60, v61 offset1:1
	ds_write2_b32 v19, v62, v63 offset0:2 offset1:3
	s_waitcnt lgkmcnt(0)
	s_barrier
	ds_read_b32 v20, v7
	ds_read_b32 v21, v7 offset:132
	ds_read_b32 v22, v7 offset:264
	ds_read_b32 v23, v7 offset:396
	ds_read_b32 v24, v7 offset:528
	ds_read_b32 v25, v7 offset:660
	ds_read_b32 v26, v7 offset:792
	ds_read_b32 v27, v7 offset:924
	s_waitcnt lgkmcnt(0)
	v_cvt_pk_bf16_f32 v28, v20, v21
	v_cvt_pk_bf16_f32 v29, v22, v23
	v_cvt_pk_bf16_f32 v30, v24, v25
	v_cvt_pk_bf16_f32 v31, v26, v27
	s_add_u32 s0, s4, s29
	s_addc_u32 s1, s5, 0
	global_store_dwordx4 v8, v[28:31], s[0:1]
	s_add_i32 s31, s6, 0x800
	s_mul_hi_u32 s7, s31, 0x1234568
	s_mul_i32 s8, s7, 225
	s_sub_u32 s8, s31, s8
	s_mul_i32 s0, s7, 0x1c2000
	s_mul_hi_u32 s1, s7, 0x1c2000
	s_lshl_b32 s29, s8, 7
	s_add_u32 s0, s0, s29
	s_addc_u32 s1, s1, 0
	s_add_u32 s0, s2, s0
	s_addc_u32 s1, s3, s1
	s_sub_u32 s29, s8, 1
	s_cmp_lt_u32 s8, 128
	s_cselect_b32 s29, s8, s29
	s_cmp_eq_u32 s8, 128
	s_cselect_b32 s29, 224, s29
	s_lshl_b32 s29, s29, 16
	s_lshl_b32 s30, s7, 11
	s_add_u32 s29, s29, s30
	s_waitcnt vmcnt(8)
	s_barrier
	ds_write2_b32 v6, v64, v65 offset1:1
	ds_write2_b32 v6, v66, v67 offset0:2 offset1:3
	v_add_u32_e32 v19, 0x1080, v6
	ds_write2_b32 v19, v68, v69 offset1:1
	ds_write2_b32 v19, v70, v71 offset0:2 offset1:3
	s_waitcnt lgkmcnt(0)
	s_barrier
	ds_read_b32 v20, v7
	ds_read_b32 v21, v7 offset:132
	ds_read_b32 v22, v7 offset:264
	ds_read_b32 v23, v7 offset:396
	ds_read_b32 v24, v7 offset:528
	ds_read_b32 v25, v7 offset:660
	ds_read_b32 v26, v7 offset:792
	ds_read_b32 v27, v7 offset:924
	s_waitcnt lgkmcnt(0)
	v_cvt_pk_bf16_f32 v28, v20, v21
	v_cvt_pk_bf16_f32 v29, v22, v23
	v_cvt_pk_bf16_f32 v30, v24, v25
	v_cvt_pk_bf16_f32 v31, v26, v27
	s_add_u32 s0, s4, s29
	s_addc_u32 s1, s5, 0
	global_store_dwordx4 v8, v[28:31], s[0:1]
	s_add_i32 s31, s6, 0xa00
	s_mul_hi_u32 s7, s31, 0x1234568
	s_mul_i32 s8, s7, 225
	s_sub_u32 s8, s31, s8
	s_mul_i32 s0, s7, 0x1c2000
	s_mul_hi_u32 s1, s7, 0x1c2000
	s_lshl_b32 s29, s8, 7
	s_add_u32 s0, s0, s29
	s_addc_u32 s1, s1, 0
	s_add_u32 s0, s2, s0
	s_addc_u32 s1, s3, s1
	s_sub_u32 s29, s8, 1
	s_cmp_lt_u32 s8, 128
	s_cselect_b32 s29, s8, s29
	s_cmp_eq_u32 s8, 128
	s_cselect_b32 s29, 224, s29
	s_lshl_b32 s29, s29, 16
	s_lshl_b32 s30, s7, 11
	s_add_u32 s29, s29, s30
	s_waitcnt vmcnt(7)
	s_barrier
	ds_write2_b32 v6, v72, v73 offset1:1
	ds_write2_b32 v6, v74, v75 offset0:2 offset1:3
	v_add_u32_e32 v19, 0x1080, v6
	ds_write2_b32 v19, v76, v77 offset1:1
	ds_write2_b32 v19, v78, v79 offset0:2 offset1:3
	s_waitcnt lgkmcnt(0)
	s_barrier
	ds_read_b32 v20, v7
	ds_read_b32 v21, v7 offset:132
	ds_read_b32 v22, v7 offset:264
	ds_read_b32 v23, v7 offset:396
	ds_read_b32 v24, v7 offset:528
	ds_read_b32 v25, v7 offset:660
	ds_read_b32 v26, v7 offset:792
	ds_read_b32 v27, v7 offset:924
	s_waitcnt lgkmcnt(0)
	v_cvt_pk_bf16_f32 v28, v20, v21
	v_cvt_pk_bf16_f32 v29, v22, v23
	v_cvt_pk_bf16_f32 v30, v24, v25
	v_cvt_pk_bf16_f32 v31, v26, v27
	s_add_u32 s0, s4, s29
	s_addc_u32 s1, s5, 0
	global_store_dwordx4 v8, v[28:31], s[0:1]
	s_add_i32 s31, s6, 0xc00
	s_mul_hi_u32 s7, s31, 0x1234568
	s_mul_i32 s8, s7, 225
	s_sub_u32 s8, s31, s8
	s_mul_i32 s0, s7, 0x1c2000
	s_mul_hi_u32 s1, s7, 0x1c2000
	s_lshl_b32 s29, s8, 7
	s_add_u32 s0, s0, s29
	s_addc_u32 s1, s1, 0
	s_add_u32 s0, s2, s0
	s_addc_u32 s1, s3, s1
	s_sub_u32 s29, s8, 1
	s_cmp_lt_u32 s8, 128
	s_cselect_b32 s29, s8, s29
	s_cmp_eq_u32 s8, 128
	s_cselect_b32 s29, 224, s29
	s_lshl_b32 s29, s29, 16
	s_lshl_b32 s30, s7, 11
	s_add_u32 s29, s29, s30
	s_waitcnt vmcnt(6)
	s_barrier
	ds_write2_b32 v6, v80, v81 offset1:1
	ds_write2_b32 v6, v82, v83 offset0:2 offset1:3
	v_add_u32_e32 v19, 0x1080, v6
	ds_write2_b32 v19, v84, v85 offset1:1
	ds_write2_b32 v19, v86, v87 offset0:2 offset1:3
	s_waitcnt lgkmcnt(0)
	s_barrier
	ds_read_b32 v20, v7
	ds_read_b32 v21, v7 offset:132
	ds_read_b32 v22, v7 offset:264
	ds_read_b32 v23, v7 offset:396
	ds_read_b32 v24, v7 offset:528
	ds_read_b32 v25, v7 offset:660
	ds_read_b32 v26, v7 offset:792
	ds_read_b32 v27, v7 offset:924
	s_waitcnt lgkmcnt(0)
	v_cvt_pk_bf16_f32 v28, v20, v21
	v_cvt_pk_bf16_f32 v29, v22, v23
	v_cvt_pk_bf16_f32 v30, v24, v25
	v_cvt_pk_bf16_f32 v31, v26, v27
	s_add_u32 s0, s4, s29
	s_addc_u32 s1, s5, 0
	global_store_dwordx4 v8, v[28:31], s[0:1]
	s_add_i32 s31, s6, 0xe00
	s_cmp_lt_u32 s31, 3600
	s_cbranch_scc0 .Lfm_a_win_done
	s_mul_hi_u32 s7, s31, 0x1234568
	s_mul_i32 s8, s7, 225
	s_sub_u32 s8, s31, s8
	s_mul_i32 s0, s7, 0x1c2000
	s_mul_hi_u32 s1, s7, 0x1c2000
	s_lshl_b32 s29, s8, 7
	s_add_u32 s0, s0, s29
	s_addc_u32 s1, s1, 0
	s_add_u32 s0, s2, s0
	s_addc_u32 s1, s3, s1
	s_sub_u32 s29, s8, 1
	s_cmp_lt_u32 s8, 128
	s_cselect_b32 s29, s8, s29
	s_cmp_eq_u32 s8, 128
	s_cselect_b32 s29, 224, s29
	s_lshl_b32 s29, s29, 16
	s_lshl_b32 s30, s7, 11
	s_add_u32 s29, s29, s30
	s_waitcnt vmcnt(5)
	s_barrier
	ds_write2_b32 v6, v88, v89 offset1:1
	ds_write2_b32 v6, v90, v91 offset0:2 offset1:3
	v_add_u32_e32 v19, 0x1080, v6
	ds_write2_b32 v19, v92, v93 offset1:1
	ds_write2_b32 v19, v94, v95 offset0:2 offset1:3
	s_waitcnt lgkmcnt(0)
	s_barrier
	ds_read_b32 v20, v7
	ds_read_b32 v21, v7 offset:132
	ds_read_b32 v22, v7 offset:264
	ds_read_b32 v23, v7 offset:396
	ds_read_b32 v24, v7 offset:528
	ds_read_b32 v25, v7 offset:660
	ds_read_b32 v26, v7 offset:792
	ds_read_b32 v27, v7 offset:924
	s_waitcnt lgkmcnt(0)
	v_cvt_pk_bf16_f32 v28, v20, v21
	v_cvt_pk_bf16_f32 v29, v22, v23
	v_cvt_pk_bf16_f32 v30, v24, v25
	v_cvt_pk_bf16_f32 v31, v26, v27
	s_add_u32 s0, s4, s29
	s_addc_u32 s1, s5, 0
	global_store_dwordx4 v8, v[28:31], s[0:1]
.Lfm_a_win_done:
	s_waitcnt vmcnt(0) lgkmcnt(0)
	s_mov_b32 s0, s26
	s_mov_b32 s1, s27
	s_mov_b64 s[2:3], 0

.LBB0_815:
	v_readlane_b32 s2, v235, 17
	v_readlane_b32 s3, v235, 18
	s_lshl_b64 s[2:3], s[2:3], 22
	s_add_u32 s2, s14, s2
	s_addc_u32 s3, s15, s3
	s_add_u32 s4, s26, 0xfd40000
	s_addc_u32 s5, s27, 0
	v_lshrrev_b32_e32 v2, 3, v163
	v_and_b32_e32 v3, 7, v163
	v_lshlrev_b32_e32 v3, 4, v3
	s_mov_b32 s0, 0x1000
	v_mul_lo_u32 v4, v2, s0
	v_add_u32_e32 v4, v4, v3
	v_add_u32_e32 v5, 0x20000, v4
	s_movk_i32 s0, 0x84
	v_mul_lo_u32 v6, v2, s0
	v_add_u32_e32 v6, v6, v3
	v_and_b32_e32 v9, 31, v163
	v_lshrrev_b32_e32 v18, 5, v163
	s_movk_i32 s0, 0x420
	v_mul_lo_u32 v7, v18, s0
	v_lshl_add_u32 v7, v9, 2, v7
	v_lshrrev_b32_e32 v19, 4, v9
	s_mov_b32 s0, 0x8000
	v_mul_lo_u32 v8, v19, s0
	v_lshrrev_b32_e32 v19, 2, v18
	v_lshl_add_u32 v8, v19, 10, v8
	v_and_b32_e32 v19, 3, v18
	v_lshl_add_u32 v8, v19, 8, v8
	v_and_b32_e32 v19, 15, v9
	v_lshl_add_u32 v8, v19, 4, v8
	v_readlane_b32 s6, v246, 0
	s_add_i32 s31, s6, 0x0
	s_lshr_b32 s7, s31, 5
	s_and_b32 s8, s31, 31
	s_mul_i32 s0, s7, 0x40000
	s_mul_hi_u32 s1, s7, 0x40000
	s_lshl_b32 s29, s8, 7
	s_add_u32 s0, s0, s29
	s_addc_u32 s1, s1, 0
	s_add_u32 s0, s2, s0
	s_addc_u32 s1, s3, s1
	s_mul_i32 s29, s8, 0x10000
	s_lshl_b32 s30, s7, 11
	s_add_u32 s29, s29, s30
	global_load_dwordx4 v[32:35], v4, s[0:1]
	global_load_dwordx4 v[36:39], v5, s[0:1]
.Lfm_a_out_issued:
	s_add_i32 s31, s6, 0x0
	s_lshr_b32 s7, s31, 5
	s_and_b32 s8, s31, 31
	s_mul_i32 s0, s7, 0x40000
	s_mul_hi_u32 s1, s7, 0x40000
	s_lshl_b32 s29, s8, 7
	s_add_u32 s0, s0, s29
	s_addc_u32 s1, s1, 0
	s_add_u32 s0, s2, s0
	s_addc_u32 s1, s3, s1
	s_mul_i32 s29, s8, 0x10000
	s_lshl_b32 s30, s7, 11
	s_add_u32 s29, s29, s30
	s_waitcnt vmcnt(0)
	s_barrier
	ds_write2_b32 v6, v32, v33 offset1:1
	ds_write2_b32 v6, v34, v35 offset0:2 offset1:3
	v_add_u32_e32 v19, 0x1080, v6
	ds_write2_b32 v19, v36, v37 offset1:1
	ds_write2_b32 v19, v38, v39 offset0:2 offset1:3
	s_waitcnt lgkmcnt(0)
	s_barrier
	ds_read_b32 v20, v7
	ds_read_b32 v21, v7 offset:132
	ds_read_b32 v22, v7 offset:264
	ds_read_b32 v23, v7 offset:396
	ds_read_b32 v24, v7 offset:528
	ds_read_b32 v25, v7 offset:660
	ds_read_b32 v26, v7 offset:792
	ds_read_b32 v27, v7 offset:924
	s_waitcnt lgkmcnt(0)
	v_cvt_pk_bf16_f32 v28, v20, v21
	v_cvt_pk_bf16_f32 v29, v22, v23
	v_cvt_pk_bf16_f32 v30, v24, v25
	v_cvt_pk_bf16_f32 v31, v26, v27
	s_add_u32 s0, s4, s29
	s_addc_u32 s1, s5, 0
	global_store_dwordx4 v8, v[28:31], s[0:1]
.Lfm_a_out_done:
	v_readlane_b32 s2, v235, 17
	v_readlane_b32 s3, v235, 18
	s_lshl_b64 s[2:3], s[2:3], 24
	s_add_u32 s2, s16, s2
	s_addc_u32 s3, s17, s3
	s_add_u32 s4, s26, 0xff40000
	s_addc_u32 s5, s27, 0
	v_lshrrev_b32_e32 v2, 3, v163
	v_and_b32_e32 v3, 7, v163
	v_lshlrev_b32_e32 v3, 4, v3
	s_mov_b32 s0, 0x4000
	v_mul_lo_u32 v4, v2, s0
	v_add_u32_e32 v4, v4, v3
	v_add_u32_e32 v5, 0x80000, v4
	s_movk_i32 s0, 0x84
	v_mul_lo_u32 v6, v2, s0
	v_add_u32_e32 v6, v6, v3
	v_and_b32_e32 v9, 31, v163
	v_lshrrev_b32_e32 v18, 5, v163
	s_movk_i32 s0, 0x420
	v_mul_lo_u32 v7, v18, s0
	v_lshl_add_u32 v7, v9, 2, v7
	v_lshrrev_b32_e32 v19, 4, v9
	s_mov_b32 s0, 0x8000
	v_mul_lo_u32 v8, v19, s0
	v_lshrrev_b32_e32 v19, 2, v18
	v_lshl_add_u32 v8, v19, 10, v8
	v_and_b32_e32 v19, 3, v18
	v_lshl_add_u32 v8, v19, 8, v8
	v_and_b32_e32 v19, 15, v9
	v_lshl_add_u32 v8, v19, 4, v8
	v_readlane_b32 s6, v246, 0
	s_add_i32 s31, s6, 0x0
	s_lshr_b32 s7, s31, 7
	s_and_b32 s8, s31, 127
	s_mul_i32 s0, s7, 0x100000
	s_mul_hi_u32 s1, s7, 0x100000
	s_lshl_b32 s29, s8, 7
	s_add_u32 s0, s0, s29
	s_addc_u32 s1, s1, 0
	s_add_u32 s0, s2, s0
	s_addc_u32 s1, s3, s1
	s_mul_i32 s29, s8, 0x10000
	s_lshl_b32 s30, s7, 11
	s_add_u32 s29, s29, s30
	global_load_dwordx4 v[32:35], v4, s[0:1]
	global_load_dwordx4 v[36:39], v5, s[0:1]
	s_add_i32 s31, s6, 0x200
	s_lshr_b32 s7, s31, 7
	s_and_b32 s8, s31, 127
	s_mul_i32 s0, s7, 0x100000
	s_mul_hi_u32 s1, s7, 0x100000
	s_lshl_b32 s29, s8, 7
	s_add_u32 s0, s0, s29
	s_addc_u32 s1, s1, 0
	s_add_u32 s0, s2, s0
	s_addc_u32 s1, s3, s1
	s_mul_i32 s29, s8, 0x10000
	s_lshl_b32 s30, s7, 11
	s_add_u32 s29, s29, s30
	global_load_dwordx4 v[40:43], v4, s[0:1]
	global_load_dwordx4 v[44:47], v5, s[0:1]
	s_add_i32 s31, s6, 0x400
	s_lshr_b32 s7, s31, 7
	s_and_b32 s8, s31, 127
	s_mul_i32 s0, s7, 0x100000
	s_mul_hi_u32 s1, s7, 0x100000
	s_lshl_b32 s29, s8, 7
	s_add_u32 s0, s0, s29
	s_addc_u32 s1, s1, 0
	s_add_u32 s0, s2, s0
	s_addc_u32 s1, s3, s1
	s_mul_i32 s29, s8, 0x10000
	s_lshl_b32 s30, s7, 11
	s_add_u32 s29, s29, s30
	global_load_dwordx4 v[48:51], v4, s[0:1]
	global_load_dwordx4 v[52:55], v5, s[0:1]
	s_add_i32 s31, s6, 0x600
	s_lshr_b32 s7, s31, 7
	s_and_b32 s8, s31, 127
	s_mul_i32 s0, s7, 0x100000
	s_mul_hi_u32 s1, s7, 0x100000
	s_lshl_b32 s29, s8, 7
	s_add_u32 s0, s0, s29
	s_addc_u32 s1, s1, 0
	s_add_u32 s0, s2, s0
	s_addc_u32 s1, s3, s1
	s_mul_i32 s29, s8, 0x10000
	s_lshl_b32 s30, s7, 11
	s_add_u32 s29, s29, s30
	global_load_dwordx4 v[56:59], v4, s[0:1]
	global_load_dwordx4 v[60:63], v5, s[0:1]
.Lfm_a_ff1_issued:
	s_add_i32 s31, s6, 0x0
	s_lshr_b32 s7, s31, 7
	s_and_b32 s8, s31, 127
	s_mul_i32 s0, s7, 0x100000
	s_mul_hi_u32 s1, s7, 0x100000
	s_lshl_b32 s29, s8, 7
	s_add_u32 s0, s0, s29
	s_addc_u32 s1, s1, 0
	s_add_u32 s0, s2, s0
	s_addc_u32 s1, s3, s1
	s_mul_i32 s29, s8, 0x10000
	s_lshl_b32 s30, s7, 11
	s_add_u32 s29, s29, s30
	s_waitcnt vmcnt(6)
	s_barrier
	ds_write2_b32 v6, v32, v33 offset1:1
	ds_write2_b32 v6, v34, v35 offset0:2 offset1:3
	v_add_u32_e32 v19, 0x1080, v6
	ds_write2_b32 v19, v36, v37 offset1:1
	ds_write2_b32 v19, v38, v39 offset0:2 offset1:3
	s_waitcnt lgkmcnt(0)
	s_barrier
	ds_read_b32 v20, v7
	ds_read_b32 v21, v7 offset:132
	ds_read_b32 v22, v7 offset:264
	ds_read_b32 v23, v7 offset:396
	ds_read_b32 v24, v7 offset:528
	ds_read_b32 v25, v7 offset:660
	ds_read_b32 v26, v7 offset:792
	ds_read_b32 v27, v7 offset:924
	s_waitcnt lgkmcnt(0)
	v_cvt_pk_bf16_f32 v28, v20, v21
	v_cvt_pk_bf16_f32 v29, v22, v23
	v_cvt_pk_bf16_f32 v30, v24, v25
	v_cvt_pk_bf16_f32 v31, v26, v27
	s_add_u32 s0, s4, s29
	s_addc_u32 s1, s5, 0
	global_store_dwordx4 v8, v[28:31], s[0:1]
	s_add_i32 s31, s6, 0x200
	s_lshr_b32 s7, s31, 7
	s_and_b32 s8, s31, 127
	s_mul_i32 s0, s7, 0x100000
	s_mul_hi_u32 s1, s7, 0x100000
	s_lshl_b32 s29, s8, 7
	s_add_u32 s0, s0, s29
	s_addc_u32 s1, s1, 0
	s_add_u32 s0, s2, s0
	s_addc_u32 s1, s3, s1
	s_mul_i32 s29, s8, 0x10000
	s_lshl_b32 s30, s7, 11
	s_add_u32 s29, s29, s30
	s_waitcnt vmcnt(5)
	s_barrier
	ds_write2_b32 v6, v40, v41 offset1:1
	ds_write2_b32 v6, v42, v43 offset0:2 offset1:3
	v_add_u32_e32 v19, 0x1080, v6
	ds_write2_b32 v19, v44, v45 offset1:1
	ds_write2_b32 v19, v46, v47 offset0:2 offset1:3
	s_waitcnt lgkmcnt(0)
	s_barrier
	ds_read_b32 v20, v7
	ds_read_b32 v21, v7 offset:132
	ds_read_b32 v22, v7 offset:264
	ds_read_b32 v23, v7 offset:396
	ds_read_b32 v24, v7 offset:528
	ds_read_b32 v25, v7 offset:660
	ds_read_b32 v26, v7 offset:792
	ds_read_b32 v27, v7 offset:924
	s_waitcnt lgkmcnt(0)
	v_cvt_pk_bf16_f32 v28, v20, v21
	v_cvt_pk_bf16_f32 v29, v22, v23
	v_cvt_pk_bf16_f32 v30, v24, v25
	v_cvt_pk_bf16_f32 v31, v26, v27
	s_add_u32 s0, s4, s29
	s_addc_u32 s1, s5, 0
	global_store_dwordx4 v8, v[28:31], s[0:1]
	s_add_i32 s31, s6, 0x400
	s_lshr_b32 s7, s31, 7
	s_and_b32 s8, s31, 127
	s_mul_i32 s0, s7, 0x100000
	s_mul_hi_u32 s1, s7, 0x100000
	s_lshl_b32 s29, s8, 7
	s_add_u32 s0, s0, s29
	s_addc_u32 s1, s1, 0
	s_add_u32 s0, s2, s0
	s_addc_u32 s1, s3, s1
	s_mul_i32 s29, s8, 0x10000
	s_lshl_b32 s30, s7, 11
	s_add_u32 s29, s29, s30
	s_waitcnt vmcnt(4)
	s_barrier
	ds_write2_b32 v6, v48, v49 offset1:1
	ds_write2_b32 v6, v50, v51 offset0:2 offset1:3
	v_add_u32_e32 v19, 0x1080, v6
	ds_write2_b32 v19, v52, v53 offset1:1
	ds_write2_b32 v19, v54, v55 offset0:2 offset1:3
	s_waitcnt lgkmcnt(0)
	s_barrier
	ds_read_b32 v20, v7
	ds_read_b32 v21, v7 offset:132
	ds_read_b32 v22, v7 offset:264
	ds_read_b32 v23, v7 offset:396
	ds_read_b32 v24, v7 offset:528
	ds_read_b32 v25, v7 offset:660
	ds_read_b32 v26, v7 offset:792
	ds_read_b32 v27, v7 offset:924
	s_waitcnt lgkmcnt(0)
	v_cvt_pk_bf16_f32 v28, v20, v21
	v_cvt_pk_bf16_f32 v29, v22, v23
	v_cvt_pk_bf16_f32 v30, v24, v25
	v_cvt_pk_bf16_f32 v31, v26, v27
	s_add_u32 s0, s4, s29
	s_addc_u32 s1, s5, 0
	global_store_dwordx4 v8, v[28:31], s[0:1]
	s_add_i32 s31, s6, 0x600
	s_lshr_b32 s7, s31, 7
	s_and_b32 s8, s31, 127
	s_mul_i32 s0, s7, 0x100000
	s_mul_hi_u32 s1, s7, 0x100000
	s_lshl_b32 s29, s8, 7
	s_add_u32 s0, s0, s29
	s_addc_u32 s1, s1, 0
	s_add_u32 s0, s2, s0
	s_addc_u32 s1, s3, s1
	s_mul_i32 s29, s8, 0x10000
	s_lshl_b32 s30, s7, 11
	s_add_u32 s29, s29, s30
	s_waitcnt vmcnt(3)
	s_barrier
	ds_write2_b32 v6, v56, v57 offset1:1
	ds_write2_b32 v6, v58, v59 offset0:2 offset1:3
	v_add_u32_e32 v19, 0x1080, v6
	ds_write2_b32 v19, v60, v61 offset1:1
	ds_write2_b32 v19, v62, v63 offset0:2 offset1:3
	s_waitcnt lgkmcnt(0)
	s_barrier
	ds_read_b32 v20, v7
	ds_read_b32 v21, v7 offset:132
	ds_read_b32 v22, v7 offset:264
	ds_read_b32 v23, v7 offset:396
	ds_read_b32 v24, v7 offset:528
	ds_read_b32 v25, v7 offset:660
	ds_read_b32 v26, v7 offset:792
	ds_read_b32 v27, v7 offset:924
	s_waitcnt lgkmcnt(0)
	v_cvt_pk_bf16_f32 v28, v20, v21
	v_cvt_pk_bf16_f32 v29, v22, v23
	v_cvt_pk_bf16_f32 v30, v24, v25
	v_cvt_pk_bf16_f32 v31, v26, v27
	s_add_u32 s0, s4, s29
	s_addc_u32 s1, s5, 0
	global_store_dwordx4 v8, v[28:31], s[0:1]
.Lfm_a_ff1_done:
	v_readlane_b32 s2, v235, 17
	v_readlane_b32 s3, v235, 18
	s_lshl_b64 s[2:3], s[2:3], 24
	s_add_u32 s2, s18, s2
	s_addc_u32 s3, s19, s3
	s_add_u32 s4, s26, 0x10740000
	s_addc_u32 s5, s27, 0
	v_lshrrev_b32_e32 v2, 3, v163
	v_and_b32_e32 v3, 7, v163
	v_lshlrev_b32_e32 v3, 4, v3
	s_mov_b32 s0, 0x1000
	v_mul_lo_u32 v4, v2, s0
	v_add_u32_e32 v4, v4, v3
	v_add_u32_e32 v5, 0x20000, v4
	s_movk_i32 s0, 0x84
	v_mul_lo_u32 v6, v2, s0
	v_add_u32_e32 v6, v6, v3
	v_and_b32_e32 v9, 31, v163
	v_lshrrev_b32_e32 v18, 5, v163
	s_movk_i32 s0, 0x420
	v_mul_lo_u32 v7, v18, s0
	v_lshl_add_u32 v7, v9, 2, v7
	v_lshrrev_b32_e32 v19, 4, v9
	s_mov_b32 s0, 0x20000
	v_mul_lo_u32 v8, v19, s0
	v_lshrrev_b32_e32 v19, 2, v18
	v_lshl_add_u32 v8, v19, 10, v8
	v_and_b32_e32 v19, 3, v18
	v_lshl_add_u32 v8, v19, 8, v8
	v_and_b32_e32 v19, 15, v9
	v_lshl_add_u32 v8, v19, 4, v8
	v_readlane_b32 s6, v246, 0
	s_add_i32 s31, s6, 0x0
	s_lshr_b32 s7, s31, 5
	s_and_b32 s8, s31, 31
	s_mul_i32 s0, s7, 0x40000
	s_mul_hi_u32 s1, s7, 0x40000
	s_lshl_b32 s29, s8, 7
	s_add_u32 s0, s0, s29
	s_addc_u32 s1, s1, 0
	s_add_u32 s0, s2, s0
	s_addc_u32 s1, s3, s1
	s_mul_i32 s29, s8, 0x40000
	s_lshl_b32 s30, s7, 11
	s_add_u32 s29, s29, s30
	global_load_dwordx4 v[32:35], v4, s[0:1]
	global_load_dwordx4 v[36:39], v5, s[0:1]
	s_add_i32 s31, s6, 0x200
	s_lshr_b32 s7, s31, 5
	s_and_b32 s8, s31, 31
	s_mul_i32 s0, s7, 0x40000
	s_mul_hi_u32 s1, s7, 0x40000
	s_lshl_b32 s29, s8, 7
	s_add_u32 s0, s0, s29
	s_addc_u32 s1, s1, 0
	s_add_u32 s0, s2, s0
	s_addc_u32 s1, s3, s1
	s_mul_i32 s29, s8, 0x40000
	s_lshl_b32 s30, s7, 11
	s_add_u32 s29, s29, s30
	global_load_dwordx4 v[40:43], v4, s[0:1]
	global_load_dwordx4 v[44:47], v5, s[0:1]
	s_add_i32 s31, s6, 0x400
	s_lshr_b32 s7, s31, 5
	s_and_b32 s8, s31, 31
	s_mul_i32 s0, s7, 0x40000
	s_mul_hi_u32 s1, s7, 0x40000
	s_lshl_b32 s29, s8, 7
	s_add_u32 s0, s0, s29
	s_addc_u32 s1, s1, 0
	s_add_u32 s0, s2, s0
	s_addc_u32 s1, s3, s1
	s_mul_i32 s29, s8, 0x40000
	s_lshl_b32 s30, s7, 11
	s_add_u32 s29, s29, s30
	global_load_dwordx4 v[48:51], v4, s[0:1]
	global_load_dwordx4 v[52:55], v5, s[0:1]
	s_add_i32 s31, s6, 0x600
	s_lshr_b32 s7, s31, 5
	s_and_b32 s8, s31, 31
	s_mul_i32 s0, s7, 0x40000
	s_mul_hi_u32 s1, s7, 0x40000
	s_lshl_b32 s29, s8, 7
	s_add_u32 s0, s0, s29
	s_addc_u32 s1, s1, 0
	s_add_u32 s0, s2, s0
	s_addc_u32 s1, s3, s1
	s_mul_i32 s29, s8, 0x40000
	s_lshl_b32 s30, s7, 11
	s_add_u32 s29, s29, s30
	global_load_dwordx4 v[56:59], v4, s[0:1]
	global_load_dwordx4 v[60:63], v5, s[0:1]
.Lfm_a_ff2_issued:
	s_add_i32 s31, s6, 0x0
	s_lshr_b32 s7, s31, 5
	s_and_b32 s8, s31, 31
	s_mul_i32 s0, s7, 0x40000
	s_mul_hi_u32 s1, s7, 0x40000
	s_lshl_b32 s29, s8, 7
	s_add_u32 s0, s0, s29
	s_addc_u32 s1, s1, 0
	s_add_u32 s0, s2, s0
	s_addc_u32 s1, s3, s1
	s_mul_i32 s29, s8, 0x40000
	s_lshl_b32 s30, s7, 11
	s_add_u32 s29, s29, s30
	s_waitcnt vmcnt(6)
	s_barrier
	ds_write2_b32 v6, v32, v33 offset1:1
	ds_write2_b32 v6, v34, v35 offset0:2 offset1:3
	v_add_u32_e32 v19, 0x1080, v6
	ds_write2_b32 v19, v36, v37 offset1:1
	ds_write2_b32 v19, v38, v39 offset0:2 offset1:3
	s_waitcnt lgkmcnt(0)
	s_barrier
	ds_read_b32 v20, v7
	ds_read_b32 v21, v7 offset:132
	ds_read_b32 v22, v7 offset:264
	ds_read_b32 v23, v7 offset:396
	ds_read_b32 v24, v7 offset:528
	ds_read_b32 v25, v7 offset:660
	ds_read_b32 v26, v7 offset:792
	ds_read_b32 v27, v7 offset:924
	s_waitcnt lgkmcnt(0)
	v_cvt_pk_bf16_f32 v28, v20, v21
	v_cvt_pk_bf16_f32 v29, v22, v23
	v_cvt_pk_bf16_f32 v30, v24, v25
	v_cvt_pk_bf16_f32 v31, v26, v27
	s_add_u32 s0, s4, s29
	s_addc_u32 s1, s5, 0
	global_store_dwordx4 v8, v[28:31], s[0:1]
	s_add_i32 s31, s6, 0x200
	s_lshr_b32 s7, s31, 5
	s_and_b32 s8, s31, 31
	s_mul_i32 s0, s7, 0x40000
	s_mul_hi_u32 s1, s7, 0x40000
	s_lshl_b32 s29, s8, 7
	s_add_u32 s0, s0, s29
	s_addc_u32 s1, s1, 0
	s_add_u32 s0, s2, s0
	s_addc_u32 s1, s3, s1
	s_mul_i32 s29, s8, 0x40000
	s_lshl_b32 s30, s7, 11
	s_add_u32 s29, s29, s30
	s_waitcnt vmcnt(5)
	s_barrier
	ds_write2_b32 v6, v40, v41 offset1:1
	ds_write2_b32 v6, v42, v43 offset0:2 offset1:3
	v_add_u32_e32 v19, 0x1080, v6
	ds_write2_b32 v19, v44, v45 offset1:1
	ds_write2_b32 v19, v46, v47 offset0:2 offset1:3
	s_waitcnt lgkmcnt(0)
	s_barrier
	ds_read_b32 v20, v7
	ds_read_b32 v21, v7 offset:132
	ds_read_b32 v22, v7 offset:264
	ds_read_b32 v23, v7 offset:396
	ds_read_b32 v24, v7 offset:528
	ds_read_b32 v25, v7 offset:660
	ds_read_b32 v26, v7 offset:792
	ds_read_b32 v27, v7 offset:924
	s_waitcnt lgkmcnt(0)
	v_cvt_pk_bf16_f32 v28, v20, v21
	v_cvt_pk_bf16_f32 v29, v22, v23
	v_cvt_pk_bf16_f32 v30, v24, v25
	v_cvt_pk_bf16_f32 v31, v26, v27
	s_add_u32 s0, s4, s29
	s_addc_u32 s1, s5, 0
	global_store_dwordx4 v8, v[28:31], s[0:1]
	s_add_i32 s31, s6, 0x400
	s_lshr_b32 s7, s31, 5
	s_and_b32 s8, s31, 31
	s_mul_i32 s0, s7, 0x40000
	s_mul_hi_u32 s1, s7, 0x40000
	s_lshl_b32 s29, s8, 7
	s_add_u32 s0, s0, s29
	s_addc_u32 s1, s1, 0
	s_add_u32 s0, s2, s0
	s_addc_u32 s1, s3, s1
	s_mul_i32 s29, s8, 0x40000
	s_lshl_b32 s30, s7, 11
	s_add_u32 s29, s29, s30
	s_waitcnt vmcnt(4)
	s_barrier
	ds_write2_b32 v6, v48, v49 offset1:1
	ds_write2_b32 v6, v50, v51 offset0:2 offset1:3
	v_add_u32_e32 v19, 0x1080, v6
	ds_write2_b32 v19, v52, v53 offset1:1
	ds_write2_b32 v19, v54, v55 offset0:2 offset1:3
	s_waitcnt lgkmcnt(0)
	s_barrier
	ds_read_b32 v20, v7
	ds_read_b32 v21, v7 offset:132
	ds_read_b32 v22, v7 offset:264
	ds_read_b32 v23, v7 offset:396
	ds_read_b32 v24, v7 offset:528
	ds_read_b32 v25, v7 offset:660
	ds_read_b32 v26, v7 offset:792
	ds_read_b32 v27, v7 offset:924
	s_waitcnt lgkmcnt(0)
	v_cvt_pk_bf16_f32 v28, v20, v21
	v_cvt_pk_bf16_f32 v29, v22, v23
	v_cvt_pk_bf16_f32 v30, v24, v25
	v_cvt_pk_bf16_f32 v31, v26, v27
	s_add_u32 s0, s4, s29
	s_addc_u32 s1, s5, 0
	global_store_dwordx4 v8, v[28:31], s[0:1]
	s_add_i32 s31, s6, 0x600
	s_lshr_b32 s7, s31, 5
	s_and_b32 s8, s31, 31
	s_mul_i32 s0, s7, 0x40000
	s_mul_hi_u32 s1, s7, 0x40000
	s_lshl_b32 s29, s8, 7
	s_add_u32 s0, s0, s29
	s_addc_u32 s1, s1, 0
	s_add_u32 s0, s2, s0
	s_addc_u32 s1, s3, s1
	s_mul_i32 s29, s8, 0x40000
	s_lshl_b32 s30, s7, 11
	s_add_u32 s29, s29, s30
	s_waitcnt vmcnt(3)
	s_barrier
	ds_write2_b32 v6, v56, v57 offset1:1
	ds_write2_b32 v6, v58, v59 offset0:2 offset1:3
	v_add_u32_e32 v19, 0x1080, v6
	ds_write2_b32 v19, v60, v61 offset1:1
	ds_write2_b32 v19, v62, v63 offset0:2 offset1:3
	s_waitcnt lgkmcnt(0)
	s_barrier
	ds_read_b32 v20, v7
	ds_read_b32 v21, v7 offset:132
	ds_read_b32 v22, v7 offset:264
	ds_read_b32 v23, v7 offset:396
	ds_read_b32 v24, v7 offset:528
	ds_read_b32 v25, v7 offset:660
	ds_read_b32 v26, v7 offset:792
	ds_read_b32 v27, v7 offset:924
	s_waitcnt lgkmcnt(0)
	v_cvt_pk_bf16_f32 v28, v20, v21
	v_cvt_pk_bf16_f32 v29, v22, v23
	v_cvt_pk_bf16_f32 v30, v24, v25
	v_cvt_pk_bf16_f32 v31, v26, v27
	s_add_u32 s0, s4, s29
	s_addc_u32 s1, s5, 0
	global_store_dwordx4 v8, v[28:31], s[0:1]

.LBB0_858:
	s_mov_b64 s[2:3], 0
	v_readlane_b32 s4, v246, 13
	s_barrier
	s_add_u32 s0, s26, s2
	v_readlane_b32 s5, v246, 14
	s_addc_u32 s1, s27, s3
	v_mov_b32_e32 v4, v163
	s_andn2_b64 vcc, exec, s[4:5]
	v_readlane_b32 s44, v235, 8
	v_readlane_b32 s45, v235, 9
	s_cbranch_vccnz .LBB0_861
	s_mov_b32 s2, s68
	s_mov_b32 s3, s69
	s_add_u32 s4, s26, 0xeb20000
	s_addc_u32 s5, s27, 0
	v_lshrrev_b32_e32 v2, 3, v163
	v_and_b32_e32 v3, 7, v163
	v_lshlrev_b32_e32 v3, 4, v3
	s_mov_b32 s0, 0x7080
	v_mul_lo_u32 v4, v2, s0
	v_add_u32_e32 v4, v4, v3
	v_add_u32_e32 v5, 0xe1000, v4
	s_movk_i32 s0, 0x84
	v_mul_lo_u32 v6, v2, s0
	v_add_u32_e32 v6, v6, v3
	v_and_b32_e32 v9, 31, v163
	v_lshrrev_b32_e32 v18, 5, v163
	s_movk_i32 s0, 0x420
	v_mul_lo_u32 v7, v18, s0
	v_lshl_add_u32 v7, v9, 2, v7
	v_lshrrev_b32_e32 v19, 4, v9
	s_mov_b32 s0, 0x8000
	v_mul_lo_u32 v8, v19, s0
	v_lshrrev_b32_e32 v19, 2, v18
	v_lshl_add_u32 v8, v19, 10, v8
	v_and_b32_e32 v19, 3, v18
	v_lshl_add_u32 v8, v19, 8, v8
	v_and_b32_e32 v19, 15, v9
	v_lshl_add_u32 v8, v19, 4, v8
	v_readlane_b32 s6, v246, 0
	s_add_i32 s31, s6, 0x0
	s_mul_hi_u32 s7, s31, 0x1234568
	s_mul_i32 s8, s7, 225
	s_sub_u32 s8, s31, s8
	s_mul_i32 s0, s7, 0x1c2000
	s_mul_hi_u32 s1, s7, 0x1c2000
	s_lshl_b32 s29, s8, 7
	s_add_u32 s0, s0, s29
	s_addc_u32 s1, s1, 0
	s_add_u32 s0, s2, s0
	s_addc_u32 s1, s3, s1
	s_sub_u32 s29, s8, 1
	s_cmp_lt_u32 s8, 128
	s_cselect_b32 s29, s8, s29
	s_cmp_eq_u32 s8, 128
	s_cselect_b32 s29, 224, s29
	s_lshl_b32 s29, s29, 16
	s_lshl_b32 s30, s7, 11
	s_add_u32 s29, s29, s30
	global_load_dwordx4 v[32:35], v4, s[0:1]
	global_load_dwordx4 v[36:39], v5, s[0:1]
	s_add_i32 s31, s6, 0x200
	s_mul_hi_u32 s7, s31, 0x1234568
	s_mul_i32 s8, s7, 225
	s_sub_u32 s8, s31, s8
	s_mul_i32 s0, s7, 0x1c2000
	s_mul_hi_u32 s1, s7, 0x1c2000
	s_lshl_b32 s29, s8, 7
	s_add_u32 s0, s0, s29
	s_addc_u32 s1, s1, 0
	s_add_u32 s0, s2, s0
	s_addc_u32 s1, s3, s1
	s_sub_u32 s29, s8, 1
	s_cmp_lt_u32 s8, 128
	s_cselect_b32 s29, s8, s29
	s_cmp_eq_u32 s8, 128
	s_cselect_b32 s29, 224, s29
	s_lshl_b32 s29, s29, 16
	s_lshl_b32 s30, s7, 11
	s_add_u32 s29, s29, s30
	global_load_dwordx4 v[40:43], v4, s[0:1]
	global_load_dwordx4 v[44:47], v5, s[0:1]
	s_add_i32 s31, s6, 0x400
	s_mul_hi_u32 s7, s31, 0x1234568
	s_mul_i32 s8, s7, 225
	s_sub_u32 s8, s31, s8
	s_mul_i32 s0, s7, 0x1c2000
	s_mul_hi_u32 s1, s7, 0x1c2000
	s_lshl_b32 s29, s8, 7
	s_add_u32 s0, s0, s29
	s_addc_u32 s1, s1, 0
	s_add_u32 s0, s2, s0
	s_addc_u32 s1, s3, s1
	s_sub_u32 s29, s8, 1
	s_cmp_lt_u32 s8, 128
	s_cselect_b32 s29, s8, s29
	s_cmp_eq_u32 s8, 128
	s_cselect_b32 s29, 224, s29
	s_lshl_b32 s29, s29, 16
	s_lshl_b32 s30, s7, 11
	s_add_u32 s29, s29, s30
	global_load_dwordx4 v[48:51], v4, s[0:1]
	global_load_dwordx4 v[52:55], v5, s[0:1]
	s_add_i32 s31, s6, 0x600
	s_mul_hi_u32 s7, s31, 0x1234568
	s_mul_i32 s8, s7, 225
	s_sub_u32 s8, s31, s8
	s_mul_i32 s0, s7, 0x1c2000
	s_mul_hi_u32 s1, s7, 0x1c2000
	s_lshl_b32 s29, s8, 7
	s_add_u32 s0, s0, s29
	s_addc_u32 s1, s1, 0
	s_add_u32 s0, s2, s0
	s_addc_u32 s1, s3, s1
	s_sub_u32 s29, s8, 1
	s_cmp_lt_u32 s8, 128
	s_cselect_b32 s29, s8, s29
	s_cmp_eq_u32 s8, 128
	s_cselect_b32 s29, 224, s29
	s_lshl_b32 s29, s29, 16
	s_lshl_b32 s30, s7, 11
	s_add_u32 s29, s29, s30
	global_load_dwordx4 v[56:59], v4, s[0:1]
	global_load_dwordx4 v[60:63], v5, s[0:1]
	s_add_i32 s31, s6, 0x800
	s_mul_hi_u32 s7, s31, 0x1234568
	s_mul_i32 s8, s7, 225
	s_sub_u32 s8, s31, s8
	s_mul_i32 s0, s7, 0x1c2000
	s_mul_hi_u32 s1, s7, 0x1c2000
	s_lshl_b32 s29, s8, 7
	s_add_u32 s0, s0, s29
	s_addc_u32 s1, s1, 0
	s_add_u32 s0, s2, s0
	s_addc_u32 s1, s3, s1
	s_sub_u32 s29, s8, 1
	s_cmp_lt_u32 s8, 128
	s_cselect_b32 s29, s8, s29
	s_cmp_eq_u32 s8, 128
	s_cselect_b32 s29, 224, s29
	s_lshl_b32 s29, s29, 16
	s_lshl_b32 s30, s7, 11
	s_add_u32 s29, s29, s30
	global_load_dwordx4 v[64:67], v4, s[0:1]
	global_load_dwordx4 v[68:71], v5, s[0:1]
	s_add_i32 s31, s6, 0xa00
	s_mul_hi_u32 s7, s31, 0x1234568
	s_mul_i32 s8, s7, 225
	s_sub_u32 s8, s31, s8
	s_mul_i32 s0, s7, 0x1c2000
	s_mul_hi_u32 s1, s7, 0x1c2000
	s_lshl_b32 s29, s8, 7
	s_add_u32 s0, s0, s29
	s_addc_u32 s1, s1, 0
	s_add_u32 s0, s2, s0
	s_addc_u32 s1, s3, s1
	s_sub_u32 s29, s8, 1
	s_cmp_lt_u32 s8, 128
	s_cselect_b32 s29, s8, s29
	s_cmp_eq_u32 s8, 128
	s_cselect_b32 s29, 224, s29
	s_lshl_b32 s29, s29, 16
	s_lshl_b32 s30, s7, 11
	s_add_u32 s29, s29, s30
	global_load_dwordx4 v[72:75], v4, s[0:1]
	global_load_dwordx4 v[76:79], v5, s[0:1]
	s_add_i32 s31, s6, 0xc00
	s_mul_hi_u32 s7, s31, 0x1234568
	s_mul_i32 s8, s7, 225
	s_sub_u32 s8, s31, s8
	s_mul_i32 s0, s7, 0x1c2000
	s_mul_hi_u32 s1, s7, 0x1c2000
	s_lshl_b32 s29, s8, 7
	s_add_u32 s0, s0, s29
	s_addc_u32 s1, s1, 0
	s_add_u32 s0, s2, s0
	s_addc_u32 s1, s3, s1
	s_sub_u32 s29, s8, 1
	s_cmp_lt_u32 s8, 128
	s_cselect_b32 s29, s8, s29
	s_cmp_eq_u32 s8, 128
	s_cselect_b32 s29, 224, s29
	s_lshl_b32 s29, s29, 16
	s_lshl_b32 s30, s7, 11
	s_add_u32 s29, s29, s30
	global_load_dwordx4 v[80:83], v4, s[0:1]
	global_load_dwordx4 v[84:87], v5, s[0:1]
	s_add_i32 s31, s6, 0xe00
	s_cmp_lt_u32 s31, 3600
	s_cbranch_scc0 .Lfm_b_win_issued
	s_mul_hi_u32 s7, s31, 0x1234568
	s_mul_i32 s8, s7, 225
	s_sub_u32 s8, s31, s8
	s_mul_i32 s0, s7, 0x1c2000
	s_mul_hi_u32 s1, s7, 0x1c2000
	s_lshl_b32 s29, s8, 7
	s_add_u32 s0, s0, s29
	s_addc_u32 s1, s1, 0
	s_add_u32 s0, s2, s0
	s_addc_u32 s1, s3, s1
	s_sub_u32 s29, s8, 1
	s_cmp_lt_u32 s8, 128
	s_cselect_b32 s29, s8, s29
	s_cmp_eq_u32 s8, 128
	s_cselect_b32 s29, 224, s29
	s_lshl_b32 s29, s29, 16
	s_lshl_b32 s30, s7, 11
	s_add_u32 s29, s29, s30
	global_load_dwordx4 v[88:91], v4, s[0:1]
	global_load_dwordx4 v[92:95], v5, s[0:1]

.LBB0_887:
	s_mov_b32 s2, s14
	s_mov_b32 s3, s15
	s_add_u32 s4, s26, 0xfd40000
	s_addc_u32 s5, s27, 0
	v_lshrrev_b32_e32 v2, 3, v163
	v_and_b32_e32 v3, 7, v163
	v_lshlrev_b32_e32 v3, 4, v3
	s_mov_b32 s0, 0x1000
	v_mul_lo_u32 v4, v2, s0
	v_add_u32_e32 v4, v4, v3
	v_add_u32_e32 v5, 0x20000, v4
	s_movk_i32 s0, 0x84
	v_mul_lo_u32 v6, v2, s0
	v_add_u32_e32 v6, v6, v3
	v_and_b32_e32 v9, 31, v163
	v_lshrrev_b32_e32 v18, 5, v163
	s_movk_i32 s0, 0x420
	v_mul_lo_u32 v7, v18, s0
	v_lshl_add_u32 v7, v9, 2, v7
	v_lshrrev_b32_e32 v19, 4, v9
	s_mov_b32 s0, 0x8000
	v_mul_lo_u32 v8, v19, s0
	v_lshrrev_b32_e32 v19, 2, v18
	v_lshl_add_u32 v8, v19, 10, v8
	v_and_b32_e32 v19, 3, v18
	v_lshl_add_u32 v8, v19, 8, v8
	v_and_b32_e32 v19, 15, v9
	v_lshl_add_u32 v8, v19, 4, v8
	v_readlane_b32 s6, v246, 0
	s_add_i32 s31, s6, 0x0
	s_lshr_b32 s7, s31, 5
	s_and_b32 s8, s31, 31
	s_mul_i32 s0, s7, 0x40000
	s_mul_hi_u32 s1, s7, 0x40000
	s_lshl_b32 s29, s8, 7
	s_add_u32 s0, s0, s29
	s_addc_u32 s1, s1, 0
	s_add_u32 s0, s2, s0
	s_addc_u32 s1, s3, s1
	s_mul_i32 s29, s8, 0x10000
	s_lshl_b32 s30, s7, 11
	s_add_u32 s29, s29, s30
	global_load_dwordx4 v[32:35], v4, s[0:1]
	global_load_dwordx4 v[36:39], v5, s[0:1]

.Lfm_b_out_done:
	s_mov_b32 s2, s16
	s_mov_b32 s3, s17
	s_add_u32 s4, s26, 0xff40000
	s_addc_u32 s5, s27, 0
	v_lshrrev_b32_e32 v2, 3, v163
	v_and_b32_e32 v3, 7, v163
	v_lshlrev_b32_e32 v3, 4, v3
	s_mov_b32 s0, 0x4000
	v_mul_lo_u32 v4, v2, s0
	v_add_u32_e32 v4, v4, v3
	v_add_u32_e32 v5, 0x80000, v4
	s_movk_i32 s0, 0x84
	v_mul_lo_u32 v6, v2, s0
	v_add_u32_e32 v6, v6, v3
	v_and_b32_e32 v9, 31, v163
	v_lshrrev_b32_e32 v18, 5, v163
	s_movk_i32 s0, 0x420
	v_mul_lo_u32 v7, v18, s0
	v_lshl_add_u32 v7, v9, 2, v7
	v_lshrrev_b32_e32 v19, 4, v9
	s_mov_b32 s0, 0x8000
	v_mul_lo_u32 v8, v19, s0
	v_lshrrev_b32_e32 v19, 2, v18
	v_lshl_add_u32 v8, v19, 10, v8
	v_and_b32_e32 v19, 3, v18
	v_lshl_add_u32 v8, v19, 8, v8
	v_and_b32_e32 v19, 15, v9
	v_lshl_add_u32 v8, v19, 4, v8
	v_readlane_b32 s6, v246, 0
	s_add_i32 s31, s6, 0x0
	s_lshr_b32 s7, s31, 7
	s_and_b32 s8, s31, 127
	s_mul_i32 s0, s7, 0x100000
	s_mul_hi_u32 s1, s7, 0x100000
	s_lshl_b32 s29, s8, 7
	s_add_u32 s0, s0, s29
	s_addc_u32 s1, s1, 0
	s_add_u32 s0, s2, s0
	s_addc_u32 s1, s3, s1
	s_mul_i32 s29, s8, 0x10000
	s_lshl_b32 s30, s7, 11
	s_add_u32 s29, s29, s30
	global_load_dwordx4 v[32:35], v4, s[0:1]
	global_load_dwordx4 v[36:39], v5, s[0:1]
	s_add_i32 s31, s6, 0x200
	s_lshr_b32 s7, s31, 7
	s_and_b32 s8, s31, 127
	s_mul_i32 s0, s7, 0x100000
	s_mul_hi_u32 s1, s7, 0x100000
	s_lshl_b32 s29, s8, 7
	s_add_u32 s0, s0, s29
	s_addc_u32 s1, s1, 0
	s_add_u32 s0, s2, s0
	s_addc_u32 s1, s3, s1
	s_mul_i32 s29, s8, 0x10000
	s_lshl_b32 s30, s7, 11
	s_add_u32 s29, s29, s30
	global_load_dwordx4 v[40:43], v4, s[0:1]
	global_load_dwordx4 v[44:47], v5, s[0:1]
	s_add_i32 s31, s6, 0x400
	s_lshr_b32 s7, s31, 7
	s_and_b32 s8, s31, 127
	s_mul_i32 s0, s7, 0x100000
	s_mul_hi_u32 s1, s7, 0x100000
	s_lshl_b32 s29, s8, 7
	s_add_u32 s0, s0, s29
	s_addc_u32 s1, s1, 0
	s_add_u32 s0, s2, s0
	s_addc_u32 s1, s3, s1
	s_mul_i32 s29, s8, 0x10000
	s_lshl_b32 s30, s7, 11
	s_add_u32 s29, s29, s30
	global_load_dwordx4 v[48:51], v4, s[0:1]
	global_load_dwordx4 v[52:55], v5, s[0:1]
	s_add_i32 s31, s6, 0x600
	s_lshr_b32 s7, s31, 7
	s_and_b32 s8, s31, 127
	s_mul_i32 s0, s7, 0x100000
	s_mul_hi_u32 s1, s7, 0x100000
	s_lshl_b32 s29, s8, 7
	s_add_u32 s0, s0, s29
	s_addc_u32 s1, s1, 0
	s_add_u32 s0, s2, s0
	s_addc_u32 s1, s3, s1
	s_mul_i32 s29, s8, 0x10000
	s_lshl_b32 s30, s7, 11
	s_add_u32 s29, s29, s30
	global_load_dwordx4 v[56:59], v4, s[0:1]
	global_load_dwordx4 v[60:63], v5, s[0:1]

.Lfm_b_ff1_done:
	s_mov_b32 s2, s18
	s_mov_b32 s3, s19
	s_add_u32 s4, s26, 0x10740000
	s_addc_u32 s5, s27, 0
	v_lshrrev_b32_e32 v2, 3, v163
	v_and_b32_e32 v3, 7, v163
	v_lshlrev_b32_e32 v3, 4, v3
	s_mov_b32 s0, 0x1000
	v_mul_lo_u32 v4, v2, s0
	v_add_u32_e32 v4, v4, v3
	v_add_u32_e32 v5, 0x20000, v4
	s_movk_i32 s0, 0x84
	v_mul_lo_u32 v6, v2, s0
	v_add_u32_e32 v6, v6, v3
	v_and_b32_e32 v9, 31, v163
	v_lshrrev_b32_e32 v18, 5, v163
	s_movk_i32 s0, 0x420
	v_mul_lo_u32 v7, v18, s0
	v_lshl_add_u32 v7, v9, 2, v7
	v_lshrrev_b32_e32 v19, 4, v9
	s_mov_b32 s0, 0x20000
	v_mul_lo_u32 v8, v19, s0
	v_lshrrev_b32_e32 v19, 2, v18
	v_lshl_add_u32 v8, v19, 10, v8
	v_and_b32_e32 v19, 3, v18
	v_lshl_add_u32 v8, v19, 8, v8
	v_and_b32_e32 v19, 15, v9
	v_lshl_add_u32 v8, v19, 4, v8
	v_readlane_b32 s6, v246, 0
	s_add_i32 s31, s6, 0x0
	s_lshr_b32 s7, s31, 5
	s_and_b32 s8, s31, 31
	s_mul_i32 s0, s7, 0x40000
	s_mul_hi_u32 s1, s7, 0x40000
	s_lshl_b32 s29, s8, 7
	s_add_u32 s0, s0, s29
	s_addc_u32 s1, s1, 0
	s_add_u32 s0, s2, s0
	s_addc_u32 s1, s3, s1
	s_mul_i32 s29, s8, 0x40000
	s_lshl_b32 s30, s7, 11
	s_add_u32 s29, s29, s30
	global_load_dwordx4 v[32:35], v4, s[0:1]
	global_load_dwordx4 v[36:39], v5, s[0:1]
	s_add_i32 s31, s6, 0x200
	s_lshr_b32 s7, s31, 5
	s_and_b32 s8, s31, 31
	s_mul_i32 s0, s7, 0x40000
	s_mul_hi_u32 s1, s7, 0x40000
	s_lshl_b32 s29, s8, 7
	s_add_u32 s0, s0, s29
	s_addc_u32 s1, s1, 0
	s_add_u32 s0, s2, s0
	s_addc_u32 s1, s3, s1
	s_mul_i32 s29, s8, 0x40000
	s_lshl_b32 s30, s7, 11
	s_add_u32 s29, s29, s30
	global_load_dwordx4 v[40:43], v4, s[0:1]
	global_load_dwordx4 v[44:47], v5, s[0:1]
	s_add_i32 s31, s6, 0x400
	s_lshr_b32 s7, s31, 5
	s_and_b32 s8, s31, 31
	s_mul_i32 s0, s7, 0x40000
	s_mul_hi_u32 s1, s7, 0x40000
	s_lshl_b32 s29, s8, 7
	s_add_u32 s0, s0, s29
	s_addc_u32 s1, s1, 0
	s_add_u32 s0, s2, s0
	s_addc_u32 s1, s3, s1
	s_mul_i32 s29, s8, 0x40000
	s_lshl_b32 s30, s7, 11
	s_add_u32 s29, s29, s30
	global_load_dwordx4 v[48:51], v4, s[0:1]
	global_load_dwordx4 v[52:55], v5, s[0:1]
	s_add_i32 s31, s6, 0x600
	s_lshr_b32 s7, s31, 5
	s_and_b32 s8, s31, 31
	s_mul_i32 s0, s7, 0x40000
	s_mul_hi_u32 s1, s7, 0x40000
	s_lshl_b32 s29, s8, 7
	s_add_u32 s0, s0, s29
	s_addc_u32 s1, s1, 0
	s_add_u32 s0, s2, s0
	s_addc_u32 s1, s3, s1
	s_mul_i32 s29, s8, 0x40000
	s_lshl_b32 s30, s7, 11
	s_add_u32 s29, s29, s30
	global_load_dwordx4 v[56:59], v4, s[0:1]
	global_load_dwordx4 v[60:63], v5, s[0:1]
